# epilogue de-serialisation: down-GEMM gate+row loads issued together (one wait), redundant store-draining waits removed from the q rope epilogue, v_pk_mov accumulator zeroing, loop-entry vmcnt(0)->vmcn
# speedup vs baseline: 1.0054x; 1.0028x over previous
.LBB0_344:
	v_lshrrev_b32_e32 v11, 1, v9
	s_waitcnt lgkmcnt(0)
	s_add_u32 s72, s4, 0x1fd00000
	v_and_b32_e32 v10, 15, v9
	v_and_b32_e32 v12, 24, v11
	s_addc_u32 s73, s5, 0
	v_lshl_or_b32 v144, s15, 6, v10
	v_lshlrev_b32_e32 v11, 1, v12
	s_lshl_b32 s4, s15, 13
	v_lshlrev_b32_e32 v9, 2, v9
	s_lshl_b32 s15, s11, 5
	v_lshl_or_b32 v10, v10, 6, v11
	v_and_b32_e32 v9, 32, v9
	s_and_b32 s74, s15, 0x60
	v_bitop3_b32 v13, v10, s4, v9 bitop3:0xde
	s_lshl_b32 s4, s74, 7
	v_bitop3_b32 v145, v10, s4, v9 bitop3:0xde
	v_add_u32_e32 v145, 0x10000, v145
	s_add_u32 s4, s28, 0x160000
	v_mov_b32_e32 v137, v3
	s_addc_u32 s5, s29, 0
	s_add_i32 m0, s61, 0x18000
	v_lshl_add_u64 v[10:11], s[4:5], 0, v[136:137]
	v_mov_b32_e32 v133, v3
	s_waitcnt vmcnt(2)
	s_barrier
	global_load_lds_dwordx4 v[10:11], off
	s_add_i32 m0, s61, 0x1a000
	v_lshl_add_u64 v[10:11], s[4:5], 0, v[132:133]
	s_add_u32 s4, s30, 0x200000
	v_mov_b32_e32 v139, v3
	s_addc_u32 s5, s31, 0
	s_add_i32 s75, s61, 0x8000
	v_mov_b32_e32 v135, v3
	global_load_lds_dwordx4 v[10:11], off
	v_lshl_add_u64 v[10:11], s[4:5], 0, v[138:139]
	s_mov_b32 m0, s75
	s_add_i32 s76, s61, 0xa000
	global_load_lds_dwordx4 v[10:11], off
	v_lshl_add_u64 v[10:11], s[4:5], 0, v[134:135]
	s_add_u32 s4, s28, 0x164000
	s_mov_b32 m0, s76
	s_addc_u32 s5, s29, 0
	global_load_lds_dwordx4 v[10:11], off
	s_add_i32 m0, s61, 0x1c000
	v_lshl_add_u64 v[10:11], s[4:5], 0, v[136:137]
	global_load_lds_dwordx4 v[10:11], off
	v_lshl_add_u64 v[10:11], s[4:5], 0, v[132:133]
	s_add_i32 m0, s61, 0x1e000
	v_lshlrev_b32_e32 v9, 10, v7
	global_load_lds_dwordx4 v[10:11], off
	v_and_b32_e32 v9, 0xfffff800, v9
	v_lshl_add_u32 v6, v6, 7, v9
	v_and_b32_e32 v7, 1, v7
	v_lshl_or_b32 v6, v7, 6, v6
	v_lshl_add_u32 v140, v8, 1, v6
	v_lshlrev_b32_e32 v6, 10, v2
	v_and_b32_e32 v6, 0xfffff800, v6
	s_waitcnt vmcnt(6)
	v_lshl_add_u32 v4, v4, 7, v6
	v_and_b32_e32 v2, 1, v2
	s_cmpk_lt_u32 s14, 0x100
	v_and_or_b32 v10, s15, 32, v12
	v_lshl_or_b32 v2, v2, 6, v4
	s_sext_i32_i16 s25, s10
	s_cselect_b64 s[10:11], -1, 0
	v_mov_b32_e32 v141, v3
	v_lshl_add_u32 v142, v5, 1, v2
	v_mov_b32_e32 v143, v3
	s_mov_b32 s77, 0
	v_add_u32_e32 v146, 0, v13
	v_lshlrev_b32_e32 v2, 1, v10
	s_barrier
	s_waitcnt vmcnt(6)
	s_branch .LBB0_347

.LBB0_349:
	s_ashr_i32 s19, s18, 31
	s_lshl_b64 s[20:21], s[18:19], 15
	s_add_u32 s20, s35, s20
	s_addc_u32 s21, s48, s21
	s_and_b64 s[22:23], s[4:5], exec
	s_cselect_b32 s19, s21, s31
	s_cselect_b32 s78, s20, s30
	s_ashr_i32 s15, s14, 31
	s_lshl_b64 s[22:23], s[14:15], 15
	s_add_u32 s22, s40, s22
	s_addc_u32 s23, s49, s23
	s_and_b64 s[26:27], s[4:5], exec
	s_cselect_b32 s27, s23, s29
	s_cselect_b32 s26, s22, s28
	s_add_u32 s28, s28, 0x2c0000
	s_addc_u32 s29, s29, 0
	s_add_u32 s30, s30, 0x204000
	v_mov_b32_e32 v8, 0
	s_addc_u32 s31, s31, 0
	s_mov_b32 s15, -2
	v_mov_b32_e32 v9, v8
	v_pk_mov_b32 v[10:11], 0, 0
	v_pk_mov_b32 v[4:5], 0, 0
	v_pk_mov_b32 v[6:7], 0, 0
	v_pk_mov_b32 v[20:21], 0, 0
	v_pk_mov_b32 v[22:23], 0, 0
	v_pk_mov_b32 v[24:25], 0, 0
	v_pk_mov_b32 v[26:27], 0, 0
	v_pk_mov_b32 v[36:37], 0, 0
	v_pk_mov_b32 v[38:39], 0, 0
	v_pk_mov_b32 v[40:41], 0, 0
	v_pk_mov_b32 v[42:43], 0, 0
	v_pk_mov_b32 v[52:53], 0, 0
	v_pk_mov_b32 v[54:55], 0, 0
	v_pk_mov_b32 v[56:57], 0, 0
	v_pk_mov_b32 v[58:59], 0, 0
	v_pk_mov_b32 v[16:17], 0, 0
	v_pk_mov_b32 v[18:19], 0, 0
	v_pk_mov_b32 v[12:13], 0, 0
	v_pk_mov_b32 v[14:15], 0, 0
	v_pk_mov_b32 v[28:29], 0, 0
	v_pk_mov_b32 v[30:31], 0, 0
	v_pk_mov_b32 v[32:33], 0, 0
	v_pk_mov_b32 v[34:35], 0, 0
	v_pk_mov_b32 v[44:45], 0, 0
	v_pk_mov_b32 v[46:47], 0, 0
	v_pk_mov_b32 v[48:49], 0, 0
	v_pk_mov_b32 v[50:51], 0, 0
	v_pk_mov_b32 v[60:61], 0, 0
	v_pk_mov_b32 v[62:63], 0, 0
	v_pk_mov_b32 v[64:65], 0, 0
	v_pk_mov_b32 v[66:67], 0, 0
	v_pk_mov_b32 v[68:69], 0, 0
	v_pk_mov_b32 v[70:71], 0, 0
	v_pk_mov_b32 v[72:73], 0, 0
	v_pk_mov_b32 v[74:75], 0, 0
	v_pk_mov_b32 v[84:85], 0, 0
	v_pk_mov_b32 v[86:87], 0, 0
	v_pk_mov_b32 v[88:89], 0, 0
	v_pk_mov_b32 v[90:91], 0, 0
	v_pk_mov_b32 v[100:101], 0, 0
	v_pk_mov_b32 v[102:103], 0, 0
	v_pk_mov_b32 v[104:105], 0, 0
	v_pk_mov_b32 v[106:107], 0, 0
	v_pk_mov_b32 v[116:117], 0, 0
	v_pk_mov_b32 v[118:119], 0, 0
	v_pk_mov_b32 v[120:121], 0, 0
	v_pk_mov_b32 v[122:123], 0, 0
	v_pk_mov_b32 v[76:77], 0, 0
	v_pk_mov_b32 v[78:79], 0, 0
	v_pk_mov_b32 v[80:81], 0, 0
	v_pk_mov_b32 v[82:83], 0, 0
	v_pk_mov_b32 v[92:93], 0, 0
	v_pk_mov_b32 v[94:95], 0, 0
	v_pk_mov_b32 v[96:97], 0, 0
	v_pk_mov_b32 v[98:99], 0, 0
	v_pk_mov_b32 v[108:109], 0, 0
	v_pk_mov_b32 v[110:111], 0, 0
	v_pk_mov_b32 v[112:113], 0, 0
	v_pk_mov_b32 v[114:115], 0, 0
	v_pk_mov_b32 v[124:125], 0, 0
	v_pk_mov_b32 v[126:127], 0, 0
	v_pk_mov_b32 v[128:129], 0, 0
	v_pk_mov_b32 v[130:131], 0, 0
	s_branch .LBB0_351

.LBB0_432:
	s_ashr_i32 s21, s20, 31
	s_lshl_b64 s[22:23], s[20:21], 15
	s_add_u32 s22, s72, s22
	s_addc_u32 s23, s73, s23
	s_and_b64 s[24:25], s[4:5], exec
	s_cselect_b32 s21, s23, s31
	s_cselect_b32 s34, s22, s30
	s_ashr_i32 s19, s18, 31
	s_lshl_b64 s[24:25], s[18:19], 15
	s_add_u32 s24, s40, s24
	s_addc_u32 s25, s74, s25
	s_and_b64 s[36:37], s[4:5], exec
	s_cselect_b32 s19, s25, s29
	s_cselect_b32 s35, s24, s28
	s_add_u32 s48, s28, 0x80000
	s_addc_u32 s49, s29, 0
	s_add_u32 s28, s30, 0x204000
	v_mov_b32_e32 v4, 0
	s_addc_u32 s29, s31, 0
	s_mov_b32 s58, -2
	v_mov_b32_e32 v5, v4
	v_mov_b32_e32 v6, v4
	v_mov_b32_e32 v7, v4
	v_mov_b32_e32 v8, v4
	v_mov_b32_e32 v9, v4
	v_mov_b32_e32 v10, v4
	v_mov_b32_e32 v11, v4
	v_mov_b32_e32 v20, v4
	v_mov_b32_e32 v21, v4
	v_mov_b32_e32 v22, v4
	v_mov_b32_e32 v23, v4
	v_mov_b32_e32 v24, v4
	v_mov_b32_e32 v25, v4
	v_mov_b32_e32 v26, v4
	v_mov_b32_e32 v27, v4
	s_waitcnt vmcnt(0)
	v_pk_mov_b32 v[36:37], 0, 0
	v_pk_mov_b32 v[38:39], 0, 0
	v_pk_mov_b32 v[40:41], 0, 0
	v_pk_mov_b32 v[42:43], 0, 0
	v_pk_mov_b32 v[52:53], 0, 0
	v_pk_mov_b32 v[54:55], 0, 0
	v_pk_mov_b32 v[56:57], 0, 0
	v_pk_mov_b32 v[58:59], 0, 0
	v_pk_mov_b32 v[12:13], 0, 0
	v_pk_mov_b32 v[14:15], 0, 0
	v_pk_mov_b32 v[16:17], 0, 0
	v_pk_mov_b32 v[18:19], 0, 0
	v_pk_mov_b32 v[28:29], 0, 0
	v_pk_mov_b32 v[30:31], 0, 0
	v_pk_mov_b32 v[32:33], 0, 0
	v_pk_mov_b32 v[34:35], 0, 0
	v_pk_mov_b32 v[44:45], 0, 0
	v_pk_mov_b32 v[46:47], 0, 0
	v_pk_mov_b32 v[48:49], 0, 0
	v_pk_mov_b32 v[50:51], 0, 0
	v_pk_mov_b32 v[60:61], 0, 0
	v_pk_mov_b32 v[62:63], 0, 0
	v_pk_mov_b32 v[64:65], 0, 0
	v_pk_mov_b32 v[66:67], 0, 0
	v_pk_mov_b32 v[68:69], 0, 0
	v_pk_mov_b32 v[70:71], 0, 0
	v_pk_mov_b32 v[72:73], 0, 0
	v_pk_mov_b32 v[74:75], 0, 0
	v_pk_mov_b32 v[76:77], 0, 0
	v_pk_mov_b32 v[78:79], 0, 0
	v_pk_mov_b32 v[84:85], 0, 0
	v_pk_mov_b32 v[86:87], 0, 0
	v_pk_mov_b32 v[100:101], 0, 0
	v_pk_mov_b32 v[102:103], 0, 0
	v_pk_mov_b32 v[104:105], 0, 0
	v_pk_mov_b32 v[106:107], 0, 0
	v_pk_mov_b32 v[116:117], 0, 0
	v_pk_mov_b32 v[118:119], 0, 0
	v_pk_mov_b32 v[120:121], 0, 0
	v_pk_mov_b32 v[122:123], 0, 0
	v_pk_mov_b32 v[80:81], 0, 0
	v_pk_mov_b32 v[82:83], 0, 0
	v_pk_mov_b32 v[88:89], 0, 0
	v_pk_mov_b32 v[90:91], 0, 0
	v_pk_mov_b32 v[92:93], 0, 0
	v_pk_mov_b32 v[94:95], 0, 0
	v_pk_mov_b32 v[96:97], 0, 0
	v_pk_mov_b32 v[98:99], 0, 0
	v_pk_mov_b32 v[108:109], 0, 0
	v_pk_mov_b32 v[110:111], 0, 0
	v_pk_mov_b32 v[112:113], 0, 0
	v_pk_mov_b32 v[114:115], 0, 0
	v_pk_mov_b32 v[124:125], 0, 0
	v_pk_mov_b32 v[126:127], 0, 0
	v_pk_mov_b32 v[128:129], 0, 0
	v_pk_mov_b32 v[130:131], 0, 0

.LBB0_438:
	v_lshl_or_b32 v140, s27, 8, v204
	v_lshl_add_u32 v144, s26, 8, v202
	s_lshl_b64 s[26:27], s[28:29], 2
	s_add_u32 s26, s17, s26
	s_addc_u32 s27, s71, s27
	v_ashrrev_i32_e32 v141, 31, v140
	v_lshl_add_u64 v[142:143], v[140:141], 2, s[26:27]
	global_load_dwordx4 v[178:181], v[142:143], off offset:16
	global_load_dwordx4 v[182:185], v[142:143], off
	global_load_dwordx4 v[170:173], v[142:143], off offset:528
	global_load_dwordx4 v[174:177], v[142:143], off offset:512
	v_lshlrev_b64 v[186:187], 1, v[140:141]
	v_ashrrev_i32_e32 v145, 31, v144
	v_lshl_add_u64 v[188:189], s[10:11], 0, v[186:187]
	v_lshlrev_b64 v[190:191], 12, v[144:145]
	s_mov_b64 s[26:27], 0x80000
	s_andn2_b64 vcc, exec, s[4:5]
	v_lshl_add_u64 v[132:133], v[188:189], 0, v[190:191]
	global_load_dwordx4 v[206:209], v[132:133], off
	global_load_dwordx4 v[156:159], v[132:133], off offset:256
	v_or_b32_e32 v132, 16, v144
	v_ashrrev_i32_e32 v133, 31, v132
	v_lshlrev_b64 v[200:201], 12, v[132:133]
	v_lshl_add_u64 v[132:133], v[188:189], 0, v[200:201]
	global_load_dwordx4 v[152:155], v[132:133], off
	global_load_dwordx4 v[148:151], v[132:133], off offset:256
	v_or_b32_e32 v132, 32, v144
	v_ashrrev_i32_e32 v133, 31, v132
	v_lshlrev_b64 v[192:193], 12, v[132:133]
	v_lshl_add_u64 v[132:133], v[188:189], 0, v[192:193]
	global_load_dwordx4 v[140:143], v[132:133], off
	s_nop 0
	global_load_dwordx4 v[132:135], v[132:133], off offset:256
	v_or_b32_e32 v136, 48, v144
	v_ashrrev_i32_e32 v137, 31, v136
	v_lshlrev_b64 v[194:195], 12, v[136:137]
	v_lshl_add_u64 v[136:137], v[188:189], 0, v[194:195]
	global_load_dwordx4 v[144:147], v[136:137], off
	s_nop 0
	global_load_dwordx4 v[136:139], v[136:137], off offset:256
	s_waitcnt vmcnt(0)
	v_pk_mul_f32 v[170:171], v[170:171], 0.5 op_sel_hi:[1,0]
	v_pk_mul_f32 v[172:173], v[172:173], 0.5 op_sel_hi:[1,0]
	v_pk_mul_f32 v[174:175], v[174:175], 0.5 op_sel_hi:[1,0]
	v_pk_mul_f32 v[176:177], v[176:177], 0.5 op_sel_hi:[1,0]
	v_pk_mul_f32 v[178:179], v[178:179], 0.5 op_sel_hi:[1,0]
	v_pk_mul_f32 v[180:181], v[180:181], 0.5 op_sel_hi:[1,0]
	v_pk_mul_f32 v[182:183], v[182:183], 0.5 op_sel_hi:[1,0]
	v_pk_mul_f32 v[184:185], v[184:185], 0.5 op_sel_hi:[1,0]
	s_waitcnt vmcnt(7)
	v_lshlrev_b32_e32 v210, 16, v206
	v_and_b32_e32 v211, 0xffff0000, v206
	v_lshlrev_b32_e32 v206, 16, v207
	v_and_b32_e32 v207, 0xffff0000, v207
	v_pk_fma_f32 v[130:131], v[130:131], v[184:185], v[206:207]
	v_pk_fma_f32 v[128:129], v[128:129], v[182:183], v[210:211]
	v_lshlrev_b32_e32 v206, 16, v208
	v_and_b32_e32 v207, 0xffff0000, v208
	v_lshlrev_b32_e32 v208, 16, v209
	v_and_b32_e32 v209, 0xffff0000, v209
	v_pk_fma_f32 v[208:209], v[126:127], v[180:181], v[208:209]
	v_pk_fma_f32 v[126:127], v[124:125], v[178:179], v[206:207]
	v_cvt_pk_bf16_f32 v124, v128, v129
	v_lshl_add_u64 v[128:129], s[10:11], 0, v[190:191]
	v_cvt_pk_bf16_f32 v125, v130, v131
	v_cvt_pk_bf16_f32 v126, v126, v127
	v_cvt_pk_bf16_f32 v127, v208, v209
	v_lshl_add_u64 v[128:129], v[128:129], 0, v[186:187]
	global_store_dwordx4 v[128:129], v[124:127], off
	s_waitcnt vmcnt(7)
	s_nop 0
	v_lshlrev_b32_e32 v124, 16, v156
	v_and_b32_e32 v125, 0xffff0000, v156
	v_lshlrev_b32_e32 v126, 16, v157
	v_and_b32_e32 v127, 0xffff0000, v157
	v_pk_fma_f32 v[122:123], v[122:123], v[176:177], v[126:127]
	v_pk_fma_f32 v[120:121], v[120:121], v[174:175], v[124:125]
	v_lshlrev_b32_e32 v124, 16, v158
	v_and_b32_e32 v125, 0xffff0000, v158
	v_lshlrev_b32_e32 v126, 16, v159
	v_and_b32_e32 v127, 0xffff0000, v159
	v_pk_fma_f32 v[126:127], v[118:119], v[172:173], v[126:127]
	v_pk_fma_f32 v[118:119], v[116:117], v[170:171], v[124:125]
	v_cvt_pk_bf16_f32 v116, v120, v121
	v_cvt_pk_bf16_f32 v117, v122, v123
	s_nop 0
	v_cvt_pk_bf16_f32 v118, v118, v119
	v_cvt_pk_bf16_f32 v119, v126, v127
	global_store_dwordx4 v[128:129], v[116:119], off offset:256
	s_waitcnt vmcnt(7)
	s_nop 0
	v_lshlrev_b32_e32 v116, 16, v152
	v_and_b32_e32 v117, 0xffff0000, v152
	v_lshlrev_b32_e32 v118, 16, v153
	v_and_b32_e32 v119, 0xffff0000, v153
	v_pk_fma_f32 v[114:115], v[114:115], v[184:185], v[118:119]
	v_pk_fma_f32 v[112:113], v[112:113], v[182:183], v[116:117]
	v_lshlrev_b32_e32 v116, 16, v154
	v_and_b32_e32 v117, 0xffff0000, v154
	v_lshlrev_b32_e32 v118, 16, v155
	v_and_b32_e32 v119, 0xffff0000, v155
	v_pk_fma_f32 v[118:119], v[110:111], v[180:181], v[118:119]
	v_pk_fma_f32 v[110:111], v[108:109], v[178:179], v[116:117]
	v_cvt_pk_bf16_f32 v108, v112, v113
	v_lshl_add_u64 v[112:113], s[10:11], 0, v[200:201]
	v_cvt_pk_bf16_f32 v109, v114, v115
	v_cvt_pk_bf16_f32 v110, v110, v111
	v_cvt_pk_bf16_f32 v111, v118, v119
	v_lshl_add_u64 v[112:113], v[112:113], 0, v[186:187]
	global_store_dwordx4 v[112:113], v[108:111], off
	s_waitcnt vmcnt(7)
	s_nop 0
	v_lshlrev_b32_e32 v108, 16, v148
	v_and_b32_e32 v109, 0xffff0000, v148
	v_lshlrev_b32_e32 v110, 16, v149
	v_and_b32_e32 v111, 0xffff0000, v149
	v_pk_fma_f32 v[106:107], v[106:107], v[176:177], v[110:111]
	v_pk_fma_f32 v[104:105], v[104:105], v[174:175], v[108:109]
	v_lshlrev_b32_e32 v108, 16, v150
	v_and_b32_e32 v109, 0xffff0000, v150
	v_lshlrev_b32_e32 v110, 16, v151
	v_and_b32_e32 v111, 0xffff0000, v151
	v_pk_fma_f32 v[110:111], v[102:103], v[172:173], v[110:111]
	v_pk_fma_f32 v[102:103], v[100:101], v[170:171], v[108:109]
	v_cvt_pk_bf16_f32 v100, v104, v105
	v_cvt_pk_bf16_f32 v101, v106, v107
	s_nop 0
	v_cvt_pk_bf16_f32 v102, v102, v103
	v_cvt_pk_bf16_f32 v103, v110, v111
	global_store_dwordx4 v[112:113], v[100:103], off offset:256
	s_waitcnt vmcnt(7)
	s_nop 0
	v_lshlrev_b32_e32 v100, 16, v140
	v_and_b32_e32 v101, 0xffff0000, v140
	v_lshlrev_b32_e32 v102, 16, v141
	v_and_b32_e32 v103, 0xffff0000, v141
	v_pk_fma_f32 v[98:99], v[98:99], v[184:185], v[102:103]
	v_pk_fma_f32 v[96:97], v[96:97], v[182:183], v[100:101]
	v_lshlrev_b32_e32 v100, 16, v142
	v_and_b32_e32 v101, 0xffff0000, v142
	v_lshlrev_b32_e32 v102, 16, v143
	v_and_b32_e32 v103, 0xffff0000, v143
	v_pk_fma_f32 v[102:103], v[94:95], v[180:181], v[102:103]
	v_pk_fma_f32 v[94:95], v[92:93], v[178:179], v[100:101]
	v_cvt_pk_bf16_f32 v92, v96, v97
	v_lshl_add_u64 v[96:97], s[10:11], 0, v[192:193]
	v_cvt_pk_bf16_f32 v93, v98, v99
	v_cvt_pk_bf16_f32 v94, v94, v95
	v_cvt_pk_bf16_f32 v95, v102, v103
	v_lshl_add_u64 v[96:97], v[96:97], 0, v[186:187]
	global_store_dwordx4 v[96:97], v[92:95], off
	s_waitcnt vmcnt(7)
	s_nop 0
	v_lshlrev_b32_e32 v92, 16, v132
	v_and_b32_e32 v93, 0xffff0000, v132
	v_lshlrev_b32_e32 v94, 16, v133
	v_and_b32_e32 v95, 0xffff0000, v133
	v_pk_fma_f32 v[86:87], v[86:87], v[176:177], v[94:95]
	v_pk_fma_f32 v[84:85], v[84:85], v[174:175], v[92:93]
	v_lshlrev_b32_e32 v92, 16, v134
	v_and_b32_e32 v93, 0xffff0000, v134
	v_lshlrev_b32_e32 v94, 16, v135
	v_and_b32_e32 v95, 0xffff0000, v135
	v_pk_fma_f32 v[94:95], v[78:79], v[172:173], v[94:95]
	v_pk_fma_f32 v[78:79], v[76:77], v[170:171], v[92:93]
	v_cvt_pk_bf16_f32 v76, v84, v85
	v_cvt_pk_bf16_f32 v77, v86, v87
	s_waitcnt vmcnt(6)
	v_lshlrev_b32_e32 v84, 16, v146
	v_cvt_pk_bf16_f32 v78, v78, v79
	v_cvt_pk_bf16_f32 v79, v94, v95
	global_store_dwordx4 v[96:97], v[76:79], off offset:256
	v_and_b32_e32 v85, 0xffff0000, v146
	v_pk_fma_f32 v[80:81], v[80:81], v[178:179], v[84:85]
	v_lshlrev_b32_e32 v76, 16, v144
	v_and_b32_e32 v77, 0xffff0000, v144
	v_lshlrev_b32_e32 v78, 16, v145
	v_and_b32_e32 v79, 0xffff0000, v145
	v_pk_fma_f32 v[78:79], v[90:91], v[184:185], v[78:79]
	v_pk_fma_f32 v[76:77], v[88:89], v[182:183], v[76:77]
	v_lshlrev_b32_e32 v86, 16, v147
	v_and_b32_e32 v87, 0xffff0000, v147
	v_cvt_pk_bf16_f32 v76, v76, v77
	v_cvt_pk_bf16_f32 v77, v78, v79
	v_cvt_pk_bf16_f32 v78, v80, v81
	v_lshl_add_u64 v[80:81], s[10:11], 0, v[194:195]
	v_pk_fma_f32 v[82:83], v[82:83], v[180:181], v[86:87]
	v_lshl_add_u64 v[80:81], v[80:81], 0, v[186:187]
	v_cvt_pk_bf16_f32 v79, v82, v83
	global_store_dwordx4 v[80:81], v[76:79], off
	v_lshl_add_u64 v[84:85], v[190:191], 0, s[26:27]
	s_mov_b64 s[26:27], 0x90000
	s_waitcnt vmcnt(7)
	v_lshlrev_b32_e32 v76, 16, v136
	v_and_b32_e32 v77, 0xffff0000, v136
	v_lshlrev_b32_e32 v78, 16, v137
	v_and_b32_e32 v79, 0xffff0000, v137
	v_pk_fma_f32 v[74:75], v[74:75], v[176:177], v[78:79]
	v_pk_fma_f32 v[72:73], v[72:73], v[174:175], v[76:77]
	v_lshlrev_b32_e32 v76, 16, v138
	v_and_b32_e32 v77, 0xffff0000, v138
	v_lshlrev_b32_e32 v78, 16, v139
	v_and_b32_e32 v79, 0xffff0000, v139
	v_pk_fma_f32 v[78:79], v[70:71], v[172:173], v[78:79]
	v_pk_fma_f32 v[70:71], v[68:69], v[170:171], v[76:77]
	v_cvt_pk_bf16_f32 v68, v72, v73
	v_cvt_pk_bf16_f32 v69, v74, v75
	v_lshl_add_u64 v[88:89], v[190:191], 0, s[26:27]
	v_cvt_pk_bf16_f32 v70, v70, v71
	v_cvt_pk_bf16_f32 v71, v78, v79
	global_store_dwordx4 v[80:81], v[68:71], off offset:256
	s_mov_b64 s[26:27], 0xa0000
	v_lshl_add_u64 v[106:107], v[190:191], 0, s[26:27]
	v_lshl_add_u64 v[68:69], v[188:189], 0, v[84:85]
	global_load_dwordx4 v[72:75], v[68:69], off
	global_load_dwordx4 v[80:83], v[68:69], off offset:256
	v_lshl_add_u64 v[68:69], v[188:189], 0, v[88:89]
	global_load_dwordx4 v[90:93], v[68:69], off
	global_load_dwordx4 v[94:97], v[68:69], off offset:256
	v_lshl_add_u64 v[68:69], v[188:189], 0, v[106:107]
	global_load_dwordx4 v[98:101], v[68:69], off
	global_load_dwordx4 v[102:105], v[68:69], off offset:256
	s_mov_b64 s[26:27], 0xb0000
	v_lshl_add_u64 v[86:87], v[190:191], 0, s[26:27]
	v_lshl_add_u64 v[68:69], v[188:189], 0, v[86:87]
	global_load_dwordx4 v[76:79], v[68:69], off
	s_nop 0
	global_load_dwordx4 v[68:71], v[68:69], off offset:256
	s_mov_b64 s[26:27], -1
	s_waitcnt vmcnt(7)
	v_lshlrev_b32_e32 v108, 16, v72
	v_and_b32_e32 v109, 0xffff0000, v72
	v_lshlrev_b32_e32 v72, 16, v73
	v_and_b32_e32 v73, 0xffff0000, v73
	v_pk_fma_f32 v[66:67], v[66:67], v[184:185], v[72:73]
	v_pk_fma_f32 v[64:65], v[64:65], v[182:183], v[108:109]
	v_lshlrev_b32_e32 v72, 16, v74
	v_and_b32_e32 v73, 0xffff0000, v74
	v_lshlrev_b32_e32 v74, 16, v75
	v_and_b32_e32 v75, 0xffff0000, v75
	v_pk_fma_f32 v[74:75], v[62:63], v[180:181], v[74:75]
	v_pk_fma_f32 v[62:63], v[60:61], v[178:179], v[72:73]
	v_cvt_pk_bf16_f32 v60, v64, v65
	v_lshl_add_u64 v[64:65], s[10:11], 0, v[84:85]
	v_cvt_pk_bf16_f32 v61, v66, v67
	v_cvt_pk_bf16_f32 v62, v62, v63
	v_cvt_pk_bf16_f32 v63, v74, v75
	v_lshl_add_u64 v[64:65], v[64:65], 0, v[186:187]
	global_store_dwordx4 v[64:65], v[60:63], off
	s_waitcnt vmcnt(7)
	s_nop 0
	v_lshlrev_b32_e32 v60, 16, v80
	v_and_b32_e32 v61, 0xffff0000, v80
	v_lshlrev_b32_e32 v62, 16, v81
	v_and_b32_e32 v63, 0xffff0000, v81
	v_pk_fma_f32 v[58:59], v[58:59], v[176:177], v[62:63]
	v_pk_fma_f32 v[56:57], v[56:57], v[174:175], v[60:61]
	v_lshlrev_b32_e32 v60, 16, v82
	v_and_b32_e32 v61, 0xffff0000, v82
	v_lshlrev_b32_e32 v62, 16, v83
	v_and_b32_e32 v63, 0xffff0000, v83
	v_pk_fma_f32 v[62:63], v[54:55], v[172:173], v[62:63]
	v_pk_fma_f32 v[54:55], v[52:53], v[170:171], v[60:61]
	v_cvt_pk_bf16_f32 v52, v56, v57
	v_cvt_pk_bf16_f32 v53, v58, v59
	s_nop 0
	v_cvt_pk_bf16_f32 v54, v54, v55
	v_cvt_pk_bf16_f32 v55, v62, v63
	global_store_dwordx4 v[64:65], v[52:55], off offset:256
	s_waitcnt vmcnt(7)
	s_nop 0
	v_lshlrev_b32_e32 v52, 16, v90
	v_and_b32_e32 v53, 0xffff0000, v90
	v_lshlrev_b32_e32 v54, 16, v91
	v_and_b32_e32 v55, 0xffff0000, v91
	v_pk_fma_f32 v[50:51], v[50:51], v[184:185], v[54:55]
	v_pk_fma_f32 v[48:49], v[48:49], v[182:183], v[52:53]
	v_lshlrev_b32_e32 v52, 16, v92
	v_and_b32_e32 v53, 0xffff0000, v92
	v_lshlrev_b32_e32 v54, 16, v93
	v_and_b32_e32 v55, 0xffff0000, v93
	v_pk_fma_f32 v[54:55], v[46:47], v[180:181], v[54:55]
	v_pk_fma_f32 v[46:47], v[44:45], v[178:179], v[52:53]
	v_cvt_pk_bf16_f32 v44, v48, v49
	v_lshl_add_u64 v[48:49], s[10:11], 0, v[88:89]
	v_cvt_pk_bf16_f32 v45, v50, v51
	v_cvt_pk_bf16_f32 v46, v46, v47
	v_cvt_pk_bf16_f32 v47, v54, v55
	v_lshl_add_u64 v[48:49], v[48:49], 0, v[186:187]
	global_store_dwordx4 v[48:49], v[44:47], off
	s_waitcnt vmcnt(7)
	s_nop 0
	v_lshlrev_b32_e32 v44, 16, v94
	v_and_b32_e32 v45, 0xffff0000, v94
	v_lshlrev_b32_e32 v46, 16, v95
	v_and_b32_e32 v47, 0xffff0000, v95
	v_pk_fma_f32 v[42:43], v[42:43], v[176:177], v[46:47]
	v_pk_fma_f32 v[40:41], v[40:41], v[174:175], v[44:45]
	v_lshlrev_b32_e32 v44, 16, v96
	v_and_b32_e32 v45, 0xffff0000, v96
	v_lshlrev_b32_e32 v46, 16, v97
	v_and_b32_e32 v47, 0xffff0000, v97
	v_pk_fma_f32 v[46:47], v[38:39], v[172:173], v[46:47]
	v_pk_fma_f32 v[38:39], v[36:37], v[170:171], v[44:45]
	v_cvt_pk_bf16_f32 v36, v40, v41
	v_cvt_pk_bf16_f32 v37, v42, v43
	s_nop 0
	v_cvt_pk_bf16_f32 v38, v38, v39
	v_cvt_pk_bf16_f32 v39, v46, v47
	global_store_dwordx4 v[48:49], v[36:39], off offset:256
	s_waitcnt vmcnt(7)
	s_nop 0
	v_lshlrev_b32_e32 v36, 16, v98
	v_and_b32_e32 v37, 0xffff0000, v98
	v_lshlrev_b32_e32 v38, 16, v99
	v_and_b32_e32 v39, 0xffff0000, v99
	v_pk_fma_f32 v[34:35], v[34:35], v[184:185], v[38:39]
	v_pk_fma_f32 v[32:33], v[32:33], v[182:183], v[36:37]
	v_lshlrev_b32_e32 v36, 16, v100
	v_and_b32_e32 v37, 0xffff0000, v100
	v_lshlrev_b32_e32 v38, 16, v101
	v_and_b32_e32 v39, 0xffff0000, v101
	v_pk_fma_f32 v[38:39], v[30:31], v[180:181], v[38:39]
	v_pk_fma_f32 v[30:31], v[28:29], v[178:179], v[36:37]
	v_cvt_pk_bf16_f32 v28, v32, v33
	v_lshl_add_u64 v[32:33], s[10:11], 0, v[106:107]
	v_cvt_pk_bf16_f32 v29, v34, v35
	v_cvt_pk_bf16_f32 v30, v30, v31
	v_cvt_pk_bf16_f32 v31, v38, v39
	v_lshl_add_u64 v[32:33], v[32:33], 0, v[186:187]
	global_store_dwordx4 v[32:33], v[28:31], off
	s_waitcnt vmcnt(7)
	s_nop 0
	v_lshlrev_b32_e32 v28, 16, v102
	v_and_b32_e32 v29, 0xffff0000, v102
	v_lshlrev_b32_e32 v30, 16, v103
	v_and_b32_e32 v31, 0xffff0000, v103
	v_pk_fma_f32 v[26:27], v[26:27], v[176:177], v[30:31]
	v_pk_fma_f32 v[24:25], v[24:25], v[174:175], v[28:29]
	v_lshlrev_b32_e32 v28, 16, v104
	v_and_b32_e32 v29, 0xffff0000, v104
	v_lshlrev_b32_e32 v30, 16, v105
	v_and_b32_e32 v31, 0xffff0000, v105
	v_pk_fma_f32 v[30:31], v[22:23], v[172:173], v[30:31]
	v_pk_fma_f32 v[22:23], v[20:21], v[170:171], v[28:29]
	v_cvt_pk_bf16_f32 v20, v24, v25
	v_cvt_pk_bf16_f32 v21, v26, v27
	s_nop 0
	v_cvt_pk_bf16_f32 v22, v22, v23
	v_cvt_pk_bf16_f32 v23, v30, v31
	global_store_dwordx4 v[32:33], v[20:23], off offset:256
	s_waitcnt vmcnt(7)
	s_nop 0
	v_lshlrev_b32_e32 v20, 16, v76
	v_and_b32_e32 v21, 0xffff0000, v76
	v_lshlrev_b32_e32 v22, 16, v77
	v_and_b32_e32 v23, 0xffff0000, v77
	v_pk_fma_f32 v[18:19], v[18:19], v[184:185], v[22:23]
	v_pk_fma_f32 v[16:17], v[16:17], v[182:183], v[20:21]
	v_lshlrev_b32_e32 v20, 16, v78
	v_and_b32_e32 v21, 0xffff0000, v78
	v_lshlrev_b32_e32 v22, 16, v79
	v_and_b32_e32 v23, 0xffff0000, v79
	v_pk_fma_f32 v[22:23], v[14:15], v[180:181], v[22:23]
	v_pk_fma_f32 v[14:15], v[12:13], v[178:179], v[20:21]
	v_cvt_pk_bf16_f32 v12, v16, v17
	v_lshl_add_u64 v[16:17], s[10:11], 0, v[86:87]
	v_cvt_pk_bf16_f32 v13, v18, v19
	v_cvt_pk_bf16_f32 v14, v14, v15
	v_cvt_pk_bf16_f32 v15, v22, v23
	v_lshl_add_u64 v[16:17], v[16:17], 0, v[186:187]
	global_store_dwordx4 v[16:17], v[12:15], off
	s_waitcnt vmcnt(7)
	s_nop 0
	v_lshlrev_b32_e32 v12, 16, v68
	v_and_b32_e32 v13, 0xffff0000, v68
	v_lshlrev_b32_e32 v14, 16, v69
	v_and_b32_e32 v15, 0xffff0000, v69
	v_pk_fma_f32 v[10:11], v[10:11], v[176:177], v[14:15]
	v_pk_fma_f32 v[8:9], v[8:9], v[174:175], v[12:13]
	v_lshlrev_b32_e32 v12, 16, v70
	v_and_b32_e32 v13, 0xffff0000, v70
	v_lshlrev_b32_e32 v14, 16, v71
	v_and_b32_e32 v15, 0xffff0000, v71
	v_pk_fma_f32 v[14:15], v[6:7], v[172:173], v[14:15]
	v_pk_fma_f32 v[6:7], v[4:5], v[170:171], v[12:13]
	v_cvt_pk_bf16_f32 v4, v8, v9
	v_cvt_pk_bf16_f32 v5, v10, v11
	s_nop 0
	v_cvt_pk_bf16_f32 v6, v6, v7
	v_cvt_pk_bf16_f32 v7, v14, v15
	global_store_dwordx4 v[16:17], v[4:7], off offset:256
	s_cbranch_vccnz .LBB0_425
	s_andn2_b64 vcc, exec, s[8:9]
	s_cbranch_vccnz .LBB0_424
	s_barrier
	s_branch .LBB0_424

.LBB0_570:
	s_waitcnt lgkmcnt(0)
	s_add_u32 s10, s78, 0x1fd00000
	s_addc_u32 s11, s79, 0
	s_add_u32 s76, s76, 0x37a00000
	s_addc_u32 s77, s77, 0
	s_add_u32 s61, s74, 0x38a00000
	v_writelane_b32 v255, s10, 52
	s_addc_u32 s58, s75, 0
	s_add_u32 s7, s72, 0x39200000
	v_writelane_b32 v255, s11, 53
	v_writelane_b32 v255, s7, 54
	s_addc_u32 s7, s73, 0
	s_add_u32 s34, s44, 0x39a00000
	s_addc_u32 s35, s45, 0
	v_writelane_b32 v255, s7, 55
	s_add_u32 s7, s36, 0x3a600000
	v_writelane_b32 v255, s7, 56
	s_addc_u32 s7, s37, 0
	v_writelane_b32 v255, s7, 57
	s_add_u32 s7, s22, 0x3c600000
	v_writelane_b32 v255, s7, 58
	s_addc_u32 s7, s23, 0
	v_writelane_b32 v255, s7, 59
	s_add_u32 s7, s20, 0x3d000000
	v_writelane_b32 v255, s7, 60
	s_addc_u32 s7, s21, 0
	v_writelane_b32 v255, s7, 61
	v_lshrrev_b32_e32 v11, 1, v9
	v_readlane_b32 s20, v255, 39
	v_readlane_b32 s21, v255, 40
	s_add_u32 s7, s18, s20
	s_addc_u32 s10, s19, s21
	s_add_u32 s86, s7, 0x9400000
	s_addc_u32 s87, s10, 0
	s_add_u32 s7, s14, s20
	s_addc_u32 s10, s15, s21
	s_add_u32 s20, s7, 0xb400000
	s_addc_u32 s21, s10, 0
	v_readlane_b32 s10, v255, 25
	v_readlane_b32 s11, v255, 26
	s_add_u32 s4, s4, s10
	s_addc_u32 s5, s5, s11
	v_and_b32_e32 v12, 24, v11
	s_add_u32 s22, s4, 0xe400000
	v_and_b32_e32 v10, 15, v9
	v_lshlrev_b32_e32 v11, 1, v12
	v_lshlrev_b32_e32 v9, 2, v9
	s_addc_u32 s23, s5, 0
	v_lshl_or_b32 v140, s70, 6, v10
	v_lshl_or_b32 v10, v10, 6, v11
	s_lshl_b32 s4, s70, 13
	v_and_b32_e32 v9, 32, v9
	v_bitop3_b32 v13, v10, s4, v9 bitop3:0xde
	s_lshl_b32 s4, s59, 5
	s_and_b32 s7, s4, 0x60
	s_lshl_b32 s4, s7, 7
	v_bitop3_b32 v143, v10, s4, v9 bitop3:0xde
	v_add_u32_e32 v143, 0x10000, v143
	s_add_u32 s4, s94, 0x70000
	v_mov_b32_e32 v135, v3
	s_addc_u32 s5, s95, 0
	s_add_i32 m0, s48, 0x18000
	v_lshl_add_u64 v[10:11], s[4:5], 0, v[134:135]
	v_mov_b32_e32 v139, v3
	s_waitcnt vmcnt(2)
	s_barrier
	global_load_lds_dwordx4 v[10:11], off
	s_add_i32 m0, s48, 0x1a000
	v_lshl_add_u64 v[10:11], s[4:5], 0, v[138:139]
	s_add_u32 s4, s96, 0x200000
	v_mov_b32_e32 v133, v3
	s_addc_u32 s5, s97, 0
	s_add_i32 s59, s48, 0x8000
	v_mov_b32_e32 v137, v3
	global_load_lds_dwordx4 v[10:11], off
	v_lshl_add_u64 v[10:11], s[4:5], 0, v[132:133]
	s_mov_b32 m0, s59
	s_add_i32 s70, s48, 0xa000
	global_load_lds_dwordx4 v[10:11], off
	v_lshl_add_u64 v[10:11], s[4:5], 0, v[136:137]
	s_add_u32 s4, s94, 0x74000
	s_mov_b32 m0, s70
	s_addc_u32 s5, s95, 0
	global_load_lds_dwordx4 v[10:11], off
	s_add_i32 m0, s48, 0x1c000
	v_lshl_add_u64 v[10:11], s[4:5], 0, v[134:135]
	global_load_lds_dwordx4 v[10:11], off
	v_lshl_add_u64 v[10:11], s[4:5], 0, v[138:139]
	s_add_i32 m0, s48, 0x1e000
	v_lshlrev_b32_e32 v9, 10, v2
	global_load_lds_dwordx4 v[10:11], off
	v_and_b32_e32 v9, 0xfffff800, v9
	v_lshl_add_u32 v4, v4, 7, v9
	v_and_b32_e32 v2, 1, v2
	v_lshl_or_b32 v2, v2, 6, v4
	v_lshl_add_u32 v158, v5, 1, v2
	v_lshlrev_b32_e32 v2, 10, v6
	v_and_b32_e32 v2, 0xfffff800, v2
	s_waitcnt vmcnt(6)
	v_lshl_add_u32 v2, v7, 7, v2
	v_and_b32_e32 v4, 1, v6
	s_cmpk_lt_u32 s82, 0x100
	v_or_b32_e32 v144, 16, v140
	v_or_b32_e32 v146, 32, v140
	v_or_b32_e32 v148, 48, v140
	v_add_u32_e32 v150, 0x80, v140
	v_add_u32_e32 v152, 0x90, v140
	v_add_u32_e32 v154, 0xa0, v140
	v_add_u32_e32 v156, 0xb0, v140
	v_lshl_or_b32 v2, v4, 6, v2
	s_cselect_b64 s[24:25], -1, 0
	v_or_b32_e32 v142, s7, v12
	v_ashrrev_i32_e32 v141, 31, v140
	v_ashrrev_i32_e32 v145, 31, v144
	v_ashrrev_i32_e32 v147, 31, v146
	v_ashrrev_i32_e32 v149, 31, v148
	v_ashrrev_i32_e32 v151, 31, v150
	v_ashrrev_i32_e32 v153, 31, v152
	v_ashrrev_i32_e32 v155, 31, v154
	v_ashrrev_i32_e32 v157, 31, v156
	s_ashr_i32 s10, s17, 31
	v_mov_b32_e32 v159, v3
	v_lshl_add_u32 v160, v8, 1, v2
	v_mov_b32_e32 v161, v3
	s_mov_b32 s11, 0
	v_add_u32_e32 v170, 0, v13
	s_barrier
	s_waitcnt vmcnt(6)
	s_branch .LBB0_573

.LBB0_575:
	s_ashr_i32 s29, s28, 31
	s_lshl_b64 s[14:15], s[28:29], 15
	s_add_u32 s30, s40, s14
	s_addc_u32 s31, s71, s15
	s_and_b64 s[14:15], s[4:5], exec
	s_cselect_b32 s7, s31, s97
	s_cselect_b32 s18, s30, s96
	s_ashr_i32 s27, s26, 31
	s_lshl_b64 s[14:15], s[26:27], 15
	s_add_u32 s44, s92, s14
	s_addc_u32 s45, s93, s15
	s_and_b64 s[14:15], s[4:5], exec
	s_cselect_b32 s37, s45, s95
	s_cselect_b32 s36, s44, s94
	s_add_u32 s94, s94, 0xe0000
	s_addc_u32 s95, s95, 0
	s_add_u32 s96, s96, 0x204000
	v_mov_b32_e32 v4, 0
	s_addc_u32 s97, s97, 0
	s_mov_b32 s19, -2
	v_mov_b32_e32 v5, v4
	v_pk_mov_b32 v[6:7], 0, 0
	v_pk_mov_b32 v[8:9], 0, 0
	v_pk_mov_b32 v[10:11], 0, 0
	v_pk_mov_b32 v[20:21], 0, 0
	v_pk_mov_b32 v[22:23], 0, 0
	v_pk_mov_b32 v[24:25], 0, 0
	v_pk_mov_b32 v[26:27], 0, 0
	v_pk_mov_b32 v[36:37], 0, 0
	v_pk_mov_b32 v[38:39], 0, 0
	v_pk_mov_b32 v[40:41], 0, 0
	v_pk_mov_b32 v[42:43], 0, 0
	v_pk_mov_b32 v[52:53], 0, 0
	v_pk_mov_b32 v[54:55], 0, 0
	v_pk_mov_b32 v[56:57], 0, 0
	v_pk_mov_b32 v[58:59], 0, 0
	v_pk_mov_b32 v[12:13], 0, 0
	v_pk_mov_b32 v[14:15], 0, 0
	v_pk_mov_b32 v[16:17], 0, 0
	v_pk_mov_b32 v[18:19], 0, 0
	v_pk_mov_b32 v[28:29], 0, 0
	v_pk_mov_b32 v[30:31], 0, 0
	v_pk_mov_b32 v[32:33], 0, 0
	v_pk_mov_b32 v[34:35], 0, 0
	v_pk_mov_b32 v[44:45], 0, 0
	v_pk_mov_b32 v[46:47], 0, 0
	v_pk_mov_b32 v[48:49], 0, 0
	v_pk_mov_b32 v[50:51], 0, 0
	v_pk_mov_b32 v[60:61], 0, 0
	v_pk_mov_b32 v[62:63], 0, 0
	v_pk_mov_b32 v[64:65], 0, 0
	v_pk_mov_b32 v[66:67], 0, 0
	v_pk_mov_b32 v[68:69], 0, 0
	v_pk_mov_b32 v[70:71], 0, 0
	v_pk_mov_b32 v[72:73], 0, 0
	v_pk_mov_b32 v[74:75], 0, 0
	v_pk_mov_b32 v[84:85], 0, 0
	v_pk_mov_b32 v[86:87], 0, 0
	v_pk_mov_b32 v[88:89], 0, 0
	v_pk_mov_b32 v[90:91], 0, 0
	v_pk_mov_b32 v[100:101], 0, 0
	v_pk_mov_b32 v[102:103], 0, 0
	v_pk_mov_b32 v[104:105], 0, 0
	v_pk_mov_b32 v[106:107], 0, 0
	v_pk_mov_b32 v[116:117], 0, 0
	v_pk_mov_b32 v[118:119], 0, 0
	v_pk_mov_b32 v[120:121], 0, 0
	v_pk_mov_b32 v[122:123], 0, 0
	v_pk_mov_b32 v[76:77], 0, 0
	v_pk_mov_b32 v[78:79], 0, 0
	v_pk_mov_b32 v[80:81], 0, 0
	v_pk_mov_b32 v[82:83], 0, 0
	v_pk_mov_b32 v[92:93], 0, 0
	v_pk_mov_b32 v[94:95], 0, 0
	v_pk_mov_b32 v[96:97], 0, 0
	v_pk_mov_b32 v[98:99], 0, 0
	v_pk_mov_b32 v[108:109], 0, 0
	v_pk_mov_b32 v[110:111], 0, 0
	v_pk_mov_b32 v[112:113], 0, 0
	v_pk_mov_b32 v[114:115], 0, 0
	v_pk_mov_b32 v[124:125], 0, 0
	v_pk_mov_b32 v[126:127], 0, 0
	v_pk_mov_b32 v[128:129], 0, 0
	v_pk_mov_b32 v[130:131], 0, 0
	s_branch .LBB0_577

.LBB0_880:
	s_ashr_i32 s21, s20, 31
	s_lshl_b64 s[22:23], s[20:21], 15
	s_add_u32 s22, s40, s22
	s_addc_u32 s23, s76, s23
	s_and_b64 s[24:25], s[4:5], exec
	s_cselect_b32 s21, s23, s47
	s_cselect_b32 s27, s22, s46
	s_ashr_i32 s19, s18, 31
	s_lshl_b64 s[24:25], s[18:19], 15
	s_add_u32 s24, s77, s24
	s_addc_u32 s25, s78, s25
	s_and_b64 s[30:31], s[4:5], exec
	s_cselect_b32 s31, s25, s37
	s_cselect_b32 s30, s24, s36
	s_add_u32 s44, s36, 0x60000
	s_addc_u32 s45, s37, 0
	s_add_u32 s46, s46, 0x204000
	v_mov_b32_e32 v4, 0
	s_addc_u32 s47, s47, 0
	s_mov_b32 s19, -2
	v_mov_b32_e32 v5, v4
	v_mov_b32_e32 v6, v4
	v_mov_b32_e32 v7, v4
	v_mov_b32_e32 v8, v4
	v_mov_b32_e32 v9, v4
	v_mov_b32_e32 v10, v4
	v_mov_b32_e32 v11, v4
	v_mov_b32_e32 v12, v4
	v_mov_b32_e32 v13, v4
	v_mov_b32_e32 v14, v4
	v_mov_b32_e32 v15, v4
	v_mov_b32_e32 v16, v4
	v_mov_b32_e32 v17, v4
	v_mov_b32_e32 v18, v4
	v_mov_b32_e32 v19, v4
	v_mov_b32_e32 v20, v4
	v_mov_b32_e32 v21, v4
	v_mov_b32_e32 v22, v4
	v_mov_b32_e32 v23, v4
	v_mov_b32_e32 v24, v4
	v_mov_b32_e32 v25, v4
	v_mov_b32_e32 v26, v4
	v_mov_b32_e32 v27, v4
	v_mov_b32_e32 v28, v4
	v_mov_b32_e32 v29, v4
	v_mov_b32_e32 v30, v4
	v_mov_b32_e32 v31, v4
	v_mov_b32_e32 v32, v4
	v_mov_b32_e32 v33, v4
	v_mov_b32_e32 v34, v4
	v_mov_b32_e32 v35, v4
	s_waitcnt vmcnt(0)
	v_pk_mov_b32 v[68:69], 0, 0
	v_pk_mov_b32 v[70:71], 0, 0
	v_pk_mov_b32 v[72:73], 0, 0
	v_pk_mov_b32 v[74:75], 0, 0
	v_pk_mov_b32 v[76:77], 0, 0
	v_pk_mov_b32 v[78:79], 0, 0
	v_pk_mov_b32 v[80:81], 0, 0
	v_pk_mov_b32 v[82:83], 0, 0
	v_pk_mov_b32 v[84:85], 0, 0
	v_pk_mov_b32 v[86:87], 0, 0
	v_pk_mov_b32 v[88:89], 0, 0
	v_pk_mov_b32 v[90:91], 0, 0
	v_pk_mov_b32 v[92:93], 0, 0
	v_pk_mov_b32 v[94:95], 0, 0
	v_pk_mov_b32 v[96:97], 0, 0
	v_pk_mov_b32 v[98:99], 0, 0
	v_pk_mov_b32 v[36:37], 0, 0
	v_pk_mov_b32 v[38:39], 0, 0
	v_pk_mov_b32 v[40:41], 0, 0
	v_pk_mov_b32 v[42:43], 0, 0
	v_pk_mov_b32 v[44:45], 0, 0
	v_pk_mov_b32 v[46:47], 0, 0
	v_pk_mov_b32 v[48:49], 0, 0
	v_pk_mov_b32 v[50:51], 0, 0
	v_pk_mov_b32 v[52:53], 0, 0
	v_pk_mov_b32 v[54:55], 0, 0
	v_pk_mov_b32 v[56:57], 0, 0
	v_pk_mov_b32 v[58:59], 0, 0
	v_pk_mov_b32 v[60:61], 0, 0
	v_pk_mov_b32 v[62:63], 0, 0
	v_pk_mov_b32 v[64:65], 0, 0
	v_pk_mov_b32 v[66:67], 0, 0
	v_pk_mov_b32 v[120:121], 0, 0
	v_pk_mov_b32 v[122:123], 0, 0
	v_pk_mov_b32 v[128:129], 0, 0
	v_pk_mov_b32 v[130:131], 0, 0
	v_pk_mov_b32 v[148:149], 0, 0
	v_pk_mov_b32 v[150:151], 0, 0
	v_pk_mov_b32 v[152:153], 0, 0
	v_pk_mov_b32 v[154:155], 0, 0
	v_pk_mov_b32 v[168:169], 0, 0
	v_pk_mov_b32 v[170:171], 0, 0
	v_pk_mov_b32 v[176:177], 0, 0
	v_pk_mov_b32 v[178:179], 0, 0
	v_pk_mov_b32 v[188:189], 0, 0
	v_pk_mov_b32 v[190:191], 0, 0
	v_pk_mov_b32 v[192:193], 0, 0
	v_pk_mov_b32 v[194:195], 0, 0
	s_branch .LBB0_882

.LBB0_890:
	s_or_b64 exec, exec, s[30:31]
	v_or_b32_e32 v2, s19, v221
	v_cvt_pk_bf16_f32 v192, v192, v193
	v_cvt_pk_bf16_f32 v193, v194, v195
	v_cvt_pk_bf16_f32 v194, v188, v189
	v_mov_b64_e32 v[188:189], s[8:9]
	v_ashrrev_i32_e32 v213, 31, v212
	v_mad_i64_i32 v[188:189], s[30:31], v2, s84, v[188:189]
	v_lshl_add_u64 v[188:189], v[212:213], 1, v[188:189]
	v_cvt_pk_bf16_f32 v195, v190, v191
	global_store_dwordx4 v[188:189], v[192:195], off
	s_and_saveexec_b64 s[30:31], s[28:29]
	s_cbranch_execz .LBB0_892
	v_pk_mul_f32 v[192:193], v[176:177], v[172:173] op_sel:[1,1] op_sel_hi:[0,1]
	v_pk_mul_f32 v[190:191], v[176:177], v[172:173]
	v_pk_fma_f32 v[176:177], v[176:177], v[172:173], v[192:193] op_sel_hi:[1,0,1]
	v_pk_mul_f32 v[230:231], v[168:169], v[164:165] op_sel:[1,1] op_sel_hi:[0,1]
	v_mul_f32_e32 v176, v179, v175
	v_pk_fma_f32 v[194:195], v[178:179], v[174:175], v[176:177] op_sel_hi:[1,1,0] neg_lo:[0,0,1] neg_hi:[0,0,1]
	v_mul_f32_e32 v176, v178, v175
	v_pk_fma_f32 v[228:229], v[178:179], v[174:175], v[176:177] op_sel:[1,0,0] op_sel_hi:[0,1,0]
	v_pk_mul_f32 v[178:179], v[168:169], v[164:165]
	v_pk_fma_f32 v[168:169], v[168:169], v[164:165], v[230:231] op_sel_hi:[1,0,1]
	v_sub_f32_e32 v176, v190, v192
	v_mul_f32_e32 v168, v171, v167
	v_pk_fma_f32 v[232:233], v[170:171], v[166:167], v[168:169] op_sel_hi:[1,1,0] neg_lo:[0,0,1] neg_hi:[0,0,1]
	v_mul_f32_e32 v168, v170, v167
	v_pk_fma_f32 v[234:235], v[170:171], v[166:167], v[168:169] op_sel:[1,0,0] op_sel_hi:[0,1,0]
	v_sub_f32_e32 v168, v178, v230
	v_mov_b32_e32 v178, v194
	v_mov_b32_e32 v179, v228
	v_mov_b32_e32 v170, v232
	v_mov_b32_e32 v171, v234
.LBB0_892:
	s_or_b64 exec, exec, s[30:31]
	v_or_b32_e32 v190, 16, v2
	v_cvt_pk_bf16_f32 v176, v176, v177
	v_cvt_pk_bf16_f32 v177, v178, v179
	v_cvt_pk_bf16_f32 v178, v168, v169
	v_mov_b64_e32 v[168:169], s[8:9]
	v_mad_i64_i32 v[168:169], s[30:31], v190, s84, v[168:169]
	v_lshl_add_u64 v[168:169], v[212:213], 1, v[168:169]
	v_cvt_pk_bf16_f32 v179, v170, v171
	global_store_dwordx4 v[168:169], v[176:179], off
	s_and_saveexec_b64 s[30:31], s[28:29]
	s_cbranch_execz .LBB0_894
	v_pk_mul_f32 v[176:177], v[152:153], v[160:161] op_sel:[1,1] op_sel_hi:[0,1]
	v_pk_mul_f32 v[170:171], v[152:153], v[160:161]
	v_pk_fma_f32 v[152:153], v[152:153], v[160:161], v[176:177] op_sel_hi:[1,0,1]
	v_pk_mul_f32 v[192:193], v[148:149], v[156:157] op_sel:[1,1] op_sel_hi:[0,1]
	v_mul_f32_e32 v152, v155, v163
	v_pk_fma_f32 v[178:179], v[154:155], v[162:163], v[152:153] op_sel_hi:[1,1,0] neg_lo:[0,0,1] neg_hi:[0,0,1]
	v_mul_f32_e32 v152, v154, v163
	v_pk_fma_f32 v[190:191], v[154:155], v[162:163], v[152:153] op_sel:[1,0,0] op_sel_hi:[0,1,0]
	v_pk_mul_f32 v[154:155], v[148:149], v[156:157]
	v_pk_fma_f32 v[148:149], v[148:149], v[156:157], v[192:193] op_sel_hi:[1,0,1]
	v_sub_f32_e32 v152, v170, v176
	v_mul_f32_e32 v148, v151, v159
	v_pk_fma_f32 v[194:195], v[150:151], v[158:159], v[148:149] op_sel_hi:[1,1,0] neg_lo:[0,0,1] neg_hi:[0,0,1]
	v_mul_f32_e32 v148, v150, v159
	v_pk_fma_f32 v[228:229], v[150:151], v[158:159], v[148:149] op_sel:[1,0,0] op_sel_hi:[0,1,0]
	v_sub_f32_e32 v148, v154, v192
	v_mov_b32_e32 v154, v178
	v_mov_b32_e32 v155, v190
	v_mov_b32_e32 v150, v194
	v_mov_b32_e32 v151, v228
.LBB0_894:
	s_or_b64 exec, exec, s[30:31]
	v_or_b32_e32 v170, 32, v2
	v_cvt_pk_bf16_f32 v152, v152, v153
	v_cvt_pk_bf16_f32 v153, v154, v155
	v_cvt_pk_bf16_f32 v154, v148, v149
	v_mov_b64_e32 v[148:149], s[8:9]
	v_mad_i64_i32 v[148:149], s[30:31], v170, s84, v[148:149]
	v_lshl_add_u64 v[148:149], v[212:213], 1, v[148:149]
	v_cvt_pk_bf16_f32 v155, v150, v151
	global_store_dwordx4 v[148:149], v[152:155], off
	s_and_saveexec_b64 s[30:31], s[28:29]
	s_cbranch_execz .LBB0_896
	v_pk_mul_f32 v[152:153], v[128:129], v[144:145] op_sel:[1,1] op_sel_hi:[0,1]
	v_pk_mul_f32 v[150:151], v[128:129], v[144:145]
	v_pk_fma_f32 v[128:129], v[128:129], v[144:145], v[152:153] op_sel_hi:[1,0,1]
	v_pk_mul_f32 v[176:177], v[120:121], v[140:141] op_sel:[1,1] op_sel_hi:[0,1]
	v_mul_f32_e32 v128, v131, v147
	v_pk_fma_f32 v[154:155], v[130:131], v[146:147], v[128:129] op_sel_hi:[1,1,0] neg_lo:[0,0,1] neg_hi:[0,0,1]
	v_mul_f32_e32 v128, v130, v147
	v_pk_fma_f32 v[170:171], v[130:131], v[146:147], v[128:129] op_sel:[1,0,0] op_sel_hi:[0,1,0]
	v_pk_mul_f32 v[130:131], v[120:121], v[140:141]
	v_pk_fma_f32 v[120:121], v[120:121], v[140:141], v[176:177] op_sel_hi:[1,0,1]
	v_sub_f32_e32 v128, v150, v152
	v_mul_f32_e32 v120, v123, v143
	v_pk_fma_f32 v[178:179], v[122:123], v[142:143], v[120:121] op_sel_hi:[1,1,0] neg_lo:[0,0,1] neg_hi:[0,0,1]
	v_mul_f32_e32 v120, v122, v143
	v_pk_fma_f32 v[190:191], v[122:123], v[142:143], v[120:121] op_sel:[1,0,0] op_sel_hi:[0,1,0]
	v_sub_f32_e32 v120, v130, v176
	v_mov_b32_e32 v130, v154
	v_mov_b32_e32 v131, v170
	v_mov_b32_e32 v122, v178
	v_mov_b32_e32 v123, v190
.LBB0_896:
	s_or_b64 exec, exec, s[30:31]
	v_or_b32_e32 v150, 48, v2
	v_cvt_pk_bf16_f32 v128, v128, v129
	v_cvt_pk_bf16_f32 v129, v130, v131
	v_cvt_pk_bf16_f32 v130, v120, v121
	v_mov_b64_e32 v[120:121], s[8:9]
	v_mad_i64_i32 v[120:121], s[30:31], v150, s84, v[120:121]
	v_lshl_add_u64 v[120:121], v[212:213], 1, v[120:121]
	v_cvt_pk_bf16_f32 v131, v122, v123
	global_store_dwordx4 v[120:121], v[128:131], off
	s_and_saveexec_b64 s[30:31], s[28:29]
	s_cbranch_execz .LBB0_898
	v_pk_mul_f32 v[128:129], v[96:97], v[136:137] op_sel:[1,1] op_sel_hi:[0,1]
	v_pk_mul_f32 v[122:123], v[96:97], v[136:137]
	v_pk_fma_f32 v[96:97], v[96:97], v[136:137], v[128:129] op_sel_hi:[1,0,1]
	v_pk_mul_f32 v[152:153], v[92:93], v[132:133] op_sel:[1,1] op_sel_hi:[0,1]
	v_mul_f32_e32 v96, v99, v139
	v_pk_fma_f32 v[130:131], v[98:99], v[138:139], v[96:97] op_sel_hi:[1,1,0] neg_lo:[0,0,1] neg_hi:[0,0,1]
	v_mul_f32_e32 v96, v98, v139
	v_pk_fma_f32 v[150:151], v[98:99], v[138:139], v[96:97] op_sel:[1,0,0] op_sel_hi:[0,1,0]
	v_pk_mul_f32 v[98:99], v[92:93], v[132:133]
	v_pk_fma_f32 v[92:93], v[92:93], v[132:133], v[152:153] op_sel_hi:[1,0,1]
	v_sub_f32_e32 v96, v122, v128
	v_mul_f32_e32 v92, v95, v135
	v_pk_fma_f32 v[154:155], v[94:95], v[134:135], v[92:93] op_sel_hi:[1,1,0] neg_lo:[0,0,1] neg_hi:[0,0,1]
	v_mul_f32_e32 v92, v94, v135
	v_pk_fma_f32 v[170:171], v[94:95], v[134:135], v[92:93] op_sel:[1,0,0] op_sel_hi:[0,1,0]
	v_sub_f32_e32 v92, v98, v152
	v_mov_b32_e32 v98, v130
	v_mov_b32_e32 v99, v150
	v_mov_b32_e32 v94, v154
	v_mov_b32_e32 v95, v170
.LBB0_898:
	s_or_b64 exec, exec, s[30:31]
	v_add_u32_e32 v122, 0x80, v2
	v_cvt_pk_bf16_f32 v96, v96, v97
	v_cvt_pk_bf16_f32 v97, v98, v99
	v_cvt_pk_bf16_f32 v98, v92, v93
	v_mov_b64_e32 v[92:93], s[8:9]
	v_mad_i64_i32 v[92:93], s[30:31], v122, s84, v[92:93]
	v_lshl_add_u64 v[92:93], v[212:213], 1, v[92:93]
	v_cvt_pk_bf16_f32 v99, v94, v95
	global_store_dwordx4 v[92:93], v[96:99], off
	s_and_saveexec_b64 s[30:31], s[28:29]
	s_cbranch_execz .LBB0_900
	v_pk_mul_f32 v[96:97], v[88:89], v[124:125] op_sel:[1,1] op_sel_hi:[0,1]
	v_pk_mul_f32 v[94:95], v[88:89], v[124:125]
	v_pk_fma_f32 v[88:89], v[88:89], v[124:125], v[96:97] op_sel_hi:[1,0,1]
	v_pk_mul_f32 v[128:129], v[84:85], v[116:117] op_sel:[1,1] op_sel_hi:[0,1]
	v_mul_f32_e32 v88, v91, v127
	v_pk_fma_f32 v[98:99], v[90:91], v[126:127], v[88:89] op_sel_hi:[1,1,0] neg_lo:[0,0,1] neg_hi:[0,0,1]
	v_mul_f32_e32 v88, v90, v127
	v_pk_fma_f32 v[122:123], v[90:91], v[126:127], v[88:89] op_sel:[1,0,0] op_sel_hi:[0,1,0]
	v_pk_mul_f32 v[90:91], v[84:85], v[116:117]
	v_pk_fma_f32 v[84:85], v[84:85], v[116:117], v[128:129] op_sel_hi:[1,0,1]
	v_sub_f32_e32 v88, v94, v96
	v_mul_f32_e32 v84, v87, v119
	v_pk_fma_f32 v[130:131], v[86:87], v[118:119], v[84:85] op_sel_hi:[1,1,0] neg_lo:[0,0,1] neg_hi:[0,0,1]
	v_mul_f32_e32 v84, v86, v119
	v_pk_fma_f32 v[150:151], v[86:87], v[118:119], v[84:85] op_sel:[1,0,0] op_sel_hi:[0,1,0]
	v_sub_f32_e32 v84, v90, v128
	v_mov_b32_e32 v90, v98
	v_mov_b32_e32 v91, v122
	v_mov_b32_e32 v86, v130
	v_mov_b32_e32 v87, v150
.LBB0_900:
	s_or_b64 exec, exec, s[30:31]
	v_add_u32_e32 v94, 0x90, v2
	v_cvt_pk_bf16_f32 v88, v88, v89
	v_cvt_pk_bf16_f32 v89, v90, v91
	v_cvt_pk_bf16_f32 v90, v84, v85
	v_mov_b64_e32 v[84:85], s[8:9]
	v_mad_i64_i32 v[84:85], s[30:31], v94, s84, v[84:85]
	v_lshl_add_u64 v[84:85], v[212:213], 1, v[84:85]
	v_cvt_pk_bf16_f32 v91, v86, v87
	global_store_dwordx4 v[84:85], v[88:91], off
	s_and_saveexec_b64 s[30:31], s[28:29]
	s_cbranch_execz .LBB0_902
	v_pk_mul_f32 v[88:89], v[80:81], v[112:113] op_sel:[1,1] op_sel_hi:[0,1]
	v_pk_mul_f32 v[86:87], v[80:81], v[112:113]
	v_pk_fma_f32 v[80:81], v[80:81], v[112:113], v[88:89] op_sel_hi:[1,0,1]
	v_pk_mul_f32 v[96:97], v[76:77], v[108:109] op_sel:[1,1] op_sel_hi:[0,1]
	v_mul_f32_e32 v80, v83, v115
	v_pk_fma_f32 v[90:91], v[82:83], v[114:115], v[80:81] op_sel_hi:[1,1,0] neg_lo:[0,0,1] neg_hi:[0,0,1]
	v_mul_f32_e32 v80, v82, v115
	v_pk_fma_f32 v[94:95], v[82:83], v[114:115], v[80:81] op_sel:[1,0,0] op_sel_hi:[0,1,0]
	v_pk_mul_f32 v[82:83], v[76:77], v[108:109]
	v_pk_fma_f32 v[76:77], v[76:77], v[108:109], v[96:97] op_sel_hi:[1,0,1]
	v_sub_f32_e32 v80, v86, v88
	v_mul_f32_e32 v76, v79, v111
	v_pk_fma_f32 v[98:99], v[78:79], v[110:111], v[76:77] op_sel_hi:[1,1,0] neg_lo:[0,0,1] neg_hi:[0,0,1]
	v_mul_f32_e32 v76, v78, v111
	v_pk_fma_f32 v[122:123], v[78:79], v[110:111], v[76:77] op_sel:[1,0,0] op_sel_hi:[0,1,0]
	v_sub_f32_e32 v76, v82, v96
	v_mov_b32_e32 v82, v90
	v_mov_b32_e32 v83, v94
	v_mov_b32_e32 v78, v98
	v_mov_b32_e32 v79, v122
.LBB0_902:
	s_or_b64 exec, exec, s[30:31]
	v_add_u32_e32 v86, 0xa0, v2
	v_cvt_pk_bf16_f32 v80, v80, v81
	v_cvt_pk_bf16_f32 v81, v82, v83
	v_cvt_pk_bf16_f32 v82, v76, v77
	v_mov_b64_e32 v[76:77], s[8:9]
	v_mad_i64_i32 v[76:77], s[30:31], v86, s84, v[76:77]
	v_lshl_add_u64 v[76:77], v[212:213], 1, v[76:77]
	v_cvt_pk_bf16_f32 v83, v78, v79
	global_store_dwordx4 v[76:77], v[80:83], off
	s_and_saveexec_b64 s[30:31], s[28:29]
	s_cbranch_execz .LBB0_904
	v_pk_mul_f32 v[80:81], v[72:73], v[104:105] op_sel:[1,1] op_sel_hi:[0,1]
	v_pk_mul_f32 v[78:79], v[72:73], v[104:105]
	v_pk_fma_f32 v[72:73], v[72:73], v[104:105], v[80:81] op_sel_hi:[1,0,1]
	v_pk_mul_f32 v[88:89], v[68:69], v[100:101] op_sel:[1,1] op_sel_hi:[0,1]
	v_mul_f32_e32 v72, v75, v107
	v_pk_fma_f32 v[82:83], v[74:75], v[106:107], v[72:73] op_sel_hi:[1,1,0] neg_lo:[0,0,1] neg_hi:[0,0,1]
	v_mul_f32_e32 v72, v74, v107
	v_pk_fma_f32 v[86:87], v[74:75], v[106:107], v[72:73] op_sel:[1,0,0] op_sel_hi:[0,1,0]
	v_pk_mul_f32 v[74:75], v[68:69], v[100:101]
	v_pk_fma_f32 v[68:69], v[68:69], v[100:101], v[88:89] op_sel_hi:[1,0,1]
	v_sub_f32_e32 v72, v78, v80
	v_mul_f32_e32 v68, v71, v103
	v_pk_fma_f32 v[90:91], v[70:71], v[102:103], v[68:69] op_sel_hi:[1,1,0] neg_lo:[0,0,1] neg_hi:[0,0,1]
	v_mul_f32_e32 v68, v70, v103
	v_pk_fma_f32 v[94:95], v[70:71], v[102:103], v[68:69] op_sel:[1,0,0] op_sel_hi:[0,1,0]
	v_sub_f32_e32 v68, v74, v88
	v_mov_b32_e32 v74, v82
	v_mov_b32_e32 v75, v86
	v_mov_b32_e32 v70, v90
	v_mov_b32_e32 v71, v94

.LBB0_908:
	s_or_b64 exec, exec, s[28:29]
	v_cvt_pk_bf16_f32 v64, v64, v65
	v_cvt_pk_bf16_f32 v65, v66, v67
	v_cvt_pk_bf16_f32 v66, v60, v61
	v_cvt_pk_bf16_f32 v67, v62, v63
	global_store_dwordx4 v[188:189], v[64:67], off offset:256
	s_and_saveexec_b64 s[28:29], s[26:27]
	s_cbranch_execz .LBB0_910
	v_mul_f32_e32 v2, v59, v175
	v_pk_fma_f32 v[64:65], v[58:59], v[174:175], v[2:3] op_sel_hi:[1,1,0] neg_lo:[0,0,1] neg_hi:[0,0,1]
	v_mul_f32_e32 v2, v58, v175
	v_pk_fma_f32 v[66:67], v[58:59], v[174:175], v[2:3] op_sel:[1,0,0] op_sel_hi:[0,1,0]
	v_mul_f32_e32 v2, v55, v167
	v_pk_mul_f32 v[62:63], v[56:57], v[172:173] op_sel:[1,1] op_sel_hi:[0,1]
	v_pk_mul_f32 v[70:71], v[52:53], v[164:165] op_sel:[1,1] op_sel_hi:[0,1]
	v_pk_fma_f32 v[72:73], v[54:55], v[166:167], v[2:3] op_sel_hi:[1,1,0] neg_lo:[0,0,1] neg_hi:[0,0,1]
	v_mul_f32_e32 v2, v54, v167
	v_pk_mul_f32 v[60:61], v[56:57], v[172:173]
	v_pk_fma_f32 v[56:57], v[56:57], v[172:173], v[62:63] op_sel_hi:[1,0,1]
	v_pk_mul_f32 v[58:59], v[52:53], v[164:165]
	v_pk_fma_f32 v[52:53], v[52:53], v[164:165], v[70:71] op_sel_hi:[1,0,1]
	v_pk_fma_f32 v[74:75], v[54:55], v[166:167], v[2:3] op_sel:[1,0,0] op_sel_hi:[0,1,0]
	v_sub_f32_e32 v56, v60, v62
	v_sub_f32_e32 v52, v58, v70
	v_mov_b32_e32 v58, v64
	v_mov_b32_e32 v59, v66
	v_mov_b32_e32 v54, v72
	v_mov_b32_e32 v55, v74
.LBB0_910:
	s_or_b64 exec, exec, s[28:29]
	v_cvt_pk_bf16_f32 v56, v56, v57
	v_cvt_pk_bf16_f32 v57, v58, v59
	v_cvt_pk_bf16_f32 v58, v52, v53
	v_cvt_pk_bf16_f32 v59, v54, v55
	global_store_dwordx4 v[168:169], v[56:59], off offset:256
	s_and_saveexec_b64 s[28:29], s[26:27]
	s_cbranch_execz .LBB0_912
	v_mul_f32_e32 v2, v51, v163
	v_pk_fma_f32 v[56:57], v[50:51], v[162:163], v[2:3] op_sel_hi:[1,1,0] neg_lo:[0,0,1] neg_hi:[0,0,1]
	v_mul_f32_e32 v2, v50, v163
	v_pk_fma_f32 v[58:59], v[50:51], v[162:163], v[2:3] op_sel:[1,0,0] op_sel_hi:[0,1,0]
	v_mul_f32_e32 v2, v47, v159
	v_pk_mul_f32 v[54:55], v[48:49], v[160:161] op_sel:[1,1] op_sel_hi:[0,1]
	v_pk_mul_f32 v[60:61], v[44:45], v[156:157] op_sel:[1,1] op_sel_hi:[0,1]
	v_pk_fma_f32 v[62:63], v[46:47], v[158:159], v[2:3] op_sel_hi:[1,1,0] neg_lo:[0,0,1] neg_hi:[0,0,1]
	v_mul_f32_e32 v2, v46, v159
	v_pk_mul_f32 v[52:53], v[48:49], v[160:161]
	v_pk_fma_f32 v[48:49], v[48:49], v[160:161], v[54:55] op_sel_hi:[1,0,1]
	v_pk_mul_f32 v[50:51], v[44:45], v[156:157]
	v_pk_fma_f32 v[44:45], v[44:45], v[156:157], v[60:61] op_sel_hi:[1,0,1]
	v_pk_fma_f32 v[64:65], v[46:47], v[158:159], v[2:3] op_sel:[1,0,0] op_sel_hi:[0,1,0]
	v_sub_f32_e32 v48, v52, v54
	v_sub_f32_e32 v44, v50, v60
	v_mov_b32_e32 v50, v56
	v_mov_b32_e32 v51, v58
	v_mov_b32_e32 v46, v62
	v_mov_b32_e32 v47, v64
.LBB0_912:
	s_or_b64 exec, exec, s[28:29]
	v_cvt_pk_bf16_f32 v48, v48, v49
	v_cvt_pk_bf16_f32 v49, v50, v51
	v_cvt_pk_bf16_f32 v50, v44, v45
	v_cvt_pk_bf16_f32 v51, v46, v47
	global_store_dwordx4 v[148:149], v[48:51], off offset:256
	s_and_saveexec_b64 s[28:29], s[26:27]
	s_cbranch_execz .LBB0_914
	v_mul_f32_e32 v2, v43, v147
	v_pk_fma_f32 v[48:49], v[42:43], v[146:147], v[2:3] op_sel_hi:[1,1,0] neg_lo:[0,0,1] neg_hi:[0,0,1]
	v_mul_f32_e32 v2, v42, v147
	v_pk_fma_f32 v[50:51], v[42:43], v[146:147], v[2:3] op_sel:[1,0,0] op_sel_hi:[0,1,0]
	v_mul_f32_e32 v2, v39, v143
	v_pk_mul_f32 v[46:47], v[40:41], v[144:145] op_sel:[1,1] op_sel_hi:[0,1]
	v_pk_mul_f32 v[52:53], v[36:37], v[140:141] op_sel:[1,1] op_sel_hi:[0,1]
	v_pk_fma_f32 v[54:55], v[38:39], v[142:143], v[2:3] op_sel_hi:[1,1,0] neg_lo:[0,0,1] neg_hi:[0,0,1]
	v_mul_f32_e32 v2, v38, v143
	v_pk_mul_f32 v[44:45], v[40:41], v[144:145]
	v_pk_fma_f32 v[40:41], v[40:41], v[144:145], v[46:47] op_sel_hi:[1,0,1]
	v_pk_mul_f32 v[42:43], v[36:37], v[140:141]
	v_pk_fma_f32 v[36:37], v[36:37], v[140:141], v[52:53] op_sel_hi:[1,0,1]
	v_pk_fma_f32 v[56:57], v[38:39], v[142:143], v[2:3] op_sel:[1,0,0] op_sel_hi:[0,1,0]
	v_sub_f32_e32 v40, v44, v46
	v_sub_f32_e32 v36, v42, v52
	v_mov_b32_e32 v42, v48
	v_mov_b32_e32 v43, v50
	v_mov_b32_e32 v38, v54
	v_mov_b32_e32 v39, v56
.LBB0_914:
	s_or_b64 exec, exec, s[28:29]
	v_cvt_pk_bf16_f32 v40, v40, v41
	v_cvt_pk_bf16_f32 v41, v42, v43
	v_cvt_pk_bf16_f32 v42, v36, v37
	v_cvt_pk_bf16_f32 v43, v38, v39
	global_store_dwordx4 v[120:121], v[40:43], off offset:256
	s_and_saveexec_b64 s[28:29], s[26:27]
	s_cbranch_execz .LBB0_916
	v_mul_f32_e32 v2, v35, v139
	v_pk_fma_f32 v[40:41], v[34:35], v[138:139], v[2:3] op_sel_hi:[1,1,0] neg_lo:[0,0,1] neg_hi:[0,0,1]
	v_mul_f32_e32 v2, v34, v139
	v_pk_fma_f32 v[42:43], v[34:35], v[138:139], v[2:3] op_sel:[1,0,0] op_sel_hi:[0,1,0]
	v_mul_f32_e32 v2, v31, v135
	v_pk_mul_f32 v[38:39], v[32:33], v[136:137] op_sel:[1,1] op_sel_hi:[0,1]
	v_pk_mul_f32 v[44:45], v[28:29], v[132:133] op_sel:[1,1] op_sel_hi:[0,1]
	v_pk_fma_f32 v[46:47], v[30:31], v[134:135], v[2:3] op_sel_hi:[1,1,0] neg_lo:[0,0,1] neg_hi:[0,0,1]
	v_mul_f32_e32 v2, v30, v135
	v_pk_mul_f32 v[36:37], v[32:33], v[136:137]
	v_pk_fma_f32 v[32:33], v[32:33], v[136:137], v[38:39] op_sel_hi:[1,0,1]
	v_pk_mul_f32 v[34:35], v[28:29], v[132:133]
	v_pk_fma_f32 v[28:29], v[28:29], v[132:133], v[44:45] op_sel_hi:[1,0,1]
	v_pk_fma_f32 v[48:49], v[30:31], v[134:135], v[2:3] op_sel:[1,0,0] op_sel_hi:[0,1,0]
	v_sub_f32_e32 v32, v36, v38
	v_sub_f32_e32 v28, v34, v44
	v_mov_b32_e32 v34, v40
	v_mov_b32_e32 v35, v42
	v_mov_b32_e32 v30, v46
	v_mov_b32_e32 v31, v48
.LBB0_916:
	s_or_b64 exec, exec, s[28:29]
	v_cvt_pk_bf16_f32 v32, v32, v33
	v_cvt_pk_bf16_f32 v33, v34, v35
	v_cvt_pk_bf16_f32 v34, v28, v29
	v_cvt_pk_bf16_f32 v35, v30, v31
	global_store_dwordx4 v[92:93], v[32:35], off offset:256
	s_and_saveexec_b64 s[28:29], s[26:27]
	s_cbranch_execz .LBB0_918
	v_mul_f32_e32 v2, v27, v127
	v_pk_fma_f32 v[32:33], v[26:27], v[126:127], v[2:3] op_sel_hi:[1,1,0] neg_lo:[0,0,1] neg_hi:[0,0,1]
	v_mul_f32_e32 v2, v26, v127
	v_pk_fma_f32 v[34:35], v[26:27], v[126:127], v[2:3] op_sel:[1,0,0] op_sel_hi:[0,1,0]
	v_mul_f32_e32 v2, v23, v119
	v_pk_mul_f32 v[30:31], v[24:25], v[124:125] op_sel:[1,1] op_sel_hi:[0,1]
	v_pk_mul_f32 v[36:37], v[20:21], v[116:117] op_sel:[1,1] op_sel_hi:[0,1]
	v_pk_fma_f32 v[38:39], v[22:23], v[118:119], v[2:3] op_sel_hi:[1,1,0] neg_lo:[0,0,1] neg_hi:[0,0,1]
	v_mul_f32_e32 v2, v22, v119
	v_pk_mul_f32 v[28:29], v[24:25], v[124:125]
	v_pk_fma_f32 v[24:25], v[24:25], v[124:125], v[30:31] op_sel_hi:[1,0,1]
	v_pk_mul_f32 v[26:27], v[20:21], v[116:117]
	v_pk_fma_f32 v[20:21], v[20:21], v[116:117], v[36:37] op_sel_hi:[1,0,1]
	v_pk_fma_f32 v[40:41], v[22:23], v[118:119], v[2:3] op_sel:[1,0,0] op_sel_hi:[0,1,0]
	v_sub_f32_e32 v24, v28, v30
	v_sub_f32_e32 v20, v26, v36
	v_mov_b32_e32 v26, v32
	v_mov_b32_e32 v27, v34
	v_mov_b32_e32 v22, v38
	v_mov_b32_e32 v23, v40
.LBB0_918:
	s_or_b64 exec, exec, s[28:29]
	v_cvt_pk_bf16_f32 v24, v24, v25
	v_cvt_pk_bf16_f32 v25, v26, v27
	v_cvt_pk_bf16_f32 v26, v20, v21
	v_cvt_pk_bf16_f32 v27, v22, v23
	global_store_dwordx4 v[84:85], v[24:27], off offset:256
	s_and_saveexec_b64 s[28:29], s[26:27]
	s_cbranch_execz .LBB0_920
	v_mul_f32_e32 v2, v19, v115
	v_pk_fma_f32 v[24:25], v[18:19], v[114:115], v[2:3] op_sel_hi:[1,1,0] neg_lo:[0,0,1] neg_hi:[0,0,1]
	v_mul_f32_e32 v2, v18, v115
	v_pk_fma_f32 v[26:27], v[18:19], v[114:115], v[2:3] op_sel:[1,0,0] op_sel_hi:[0,1,0]
	v_mul_f32_e32 v2, v15, v111
	v_pk_mul_f32 v[22:23], v[16:17], v[112:113] op_sel:[1,1] op_sel_hi:[0,1]
	v_pk_mul_f32 v[28:29], v[12:13], v[108:109] op_sel:[1,1] op_sel_hi:[0,1]
	v_pk_fma_f32 v[30:31], v[14:15], v[110:111], v[2:3] op_sel_hi:[1,1,0] neg_lo:[0,0,1] neg_hi:[0,0,1]
	v_mul_f32_e32 v2, v14, v111
	v_pk_mul_f32 v[20:21], v[16:17], v[112:113]
	v_pk_fma_f32 v[16:17], v[16:17], v[112:113], v[22:23] op_sel_hi:[1,0,1]
	v_pk_mul_f32 v[18:19], v[12:13], v[108:109]
	v_pk_fma_f32 v[12:13], v[12:13], v[108:109], v[28:29] op_sel_hi:[1,0,1]
	v_pk_fma_f32 v[32:33], v[14:15], v[110:111], v[2:3] op_sel:[1,0,0] op_sel_hi:[0,1,0]
	v_sub_f32_e32 v16, v20, v22
	v_sub_f32_e32 v12, v18, v28
	v_mov_b32_e32 v18, v24
	v_mov_b32_e32 v19, v26
	v_mov_b32_e32 v14, v30
	v_mov_b32_e32 v15, v32
.LBB0_920:
	s_or_b64 exec, exec, s[28:29]
	v_cvt_pk_bf16_f32 v16, v16, v17
	v_cvt_pk_bf16_f32 v17, v18, v19
	v_cvt_pk_bf16_f32 v18, v12, v13
	v_cvt_pk_bf16_f32 v19, v14, v15
	global_store_dwordx4 v[76:77], v[16:19], off offset:256
	s_and_saveexec_b64 s[28:29], s[26:27]
	s_cbranch_execz .LBB0_922
	v_mul_f32_e32 v2, v11, v107
	v_pk_fma_f32 v[16:17], v[10:11], v[106:107], v[2:3] op_sel_hi:[1,1,0] neg_lo:[0,0,1] neg_hi:[0,0,1]
	v_mul_f32_e32 v2, v10, v107
	v_pk_fma_f32 v[18:19], v[10:11], v[106:107], v[2:3] op_sel:[1,0,0] op_sel_hi:[0,1,0]
	v_mul_f32_e32 v2, v7, v103
	v_pk_mul_f32 v[14:15], v[8:9], v[104:105] op_sel:[1,1] op_sel_hi:[0,1]
	v_pk_mul_f32 v[20:21], v[4:5], v[100:101] op_sel:[1,1] op_sel_hi:[0,1]
	v_pk_fma_f32 v[22:23], v[6:7], v[102:103], v[2:3] op_sel_hi:[1,1,0] neg_lo:[0,0,1] neg_hi:[0,0,1]
	v_mul_f32_e32 v2, v6, v103
	v_pk_mul_f32 v[12:13], v[8:9], v[104:105]
	v_pk_fma_f32 v[8:9], v[8:9], v[104:105], v[14:15] op_sel_hi:[1,0,1]
	v_pk_mul_f32 v[10:11], v[4:5], v[100:101]
	v_pk_fma_f32 v[4:5], v[4:5], v[100:101], v[20:21] op_sel_hi:[1,0,1]
	v_pk_fma_f32 v[24:25], v[6:7], v[102:103], v[2:3] op_sel:[1,0,0] op_sel_hi:[0,1,0]
	v_sub_f32_e32 v8, v12, v14
	v_sub_f32_e32 v4, v10, v20
	v_mov_b32_e32 v10, v16
	v_mov_b32_e32 v11, v18
	v_mov_b32_e32 v6, v22
	v_mov_b32_e32 v7, v24

.LBB0_934:
	s_ashr_i32 s25, s24, 31
	s_lshl_b64 s[26:27], s[24:25], 15
	s_add_u32 s26, s34, s26
	s_addc_u32 s27, s35, s27
	s_and_b64 s[28:29], s[4:5], exec
	s_cselect_b32 s73, s27, s47
	s_cselect_b32 s72, s26, s46
	s_ashr_i32 s23, s22, 31
	s_lshl_b64 s[28:29], s[22:23], 15
	s_add_u32 s28, s48, s28
	s_addc_u32 s29, s49, s29
	s_and_b64 s[36:37], s[4:5], exec
	v_mov_b32_e32 v4, 0
	s_cselect_b32 s23, s29, s45
	s_cselect_b32 s25, s28, s44
	s_mov_b32 s82, 0
	v_mov_b32_e32 v5, v4
	v_pk_mov_b32 v[6:7], 0, 0
	v_pk_mov_b32 v[8:9], 0, 0
	v_pk_mov_b32 v[10:11], 0, 0
	v_pk_mov_b32 v[12:13], 0, 0
	v_pk_mov_b32 v[14:15], 0, 0
	v_pk_mov_b32 v[20:21], 0, 0
	v_pk_mov_b32 v[22:23], 0, 0
	v_pk_mov_b32 v[28:29], 0, 0
	v_pk_mov_b32 v[30:31], 0, 0
	v_pk_mov_b32 v[36:37], 0, 0
	v_pk_mov_b32 v[38:39], 0, 0
	v_pk_mov_b32 v[44:45], 0, 0
	v_pk_mov_b32 v[46:47], 0, 0
	v_pk_mov_b32 v[52:53], 0, 0
	v_pk_mov_b32 v[54:55], 0, 0
	v_pk_mov_b32 v[16:17], 0, 0
	v_pk_mov_b32 v[18:19], 0, 0
	v_pk_mov_b32 v[24:25], 0, 0
	v_pk_mov_b32 v[26:27], 0, 0
	v_pk_mov_b32 v[32:33], 0, 0
	v_pk_mov_b32 v[34:35], 0, 0
	v_pk_mov_b32 v[40:41], 0, 0
	v_pk_mov_b32 v[42:43], 0, 0
	v_pk_mov_b32 v[48:49], 0, 0
	v_pk_mov_b32 v[50:51], 0, 0
	v_pk_mov_b32 v[56:57], 0, 0
	v_pk_mov_b32 v[58:59], 0, 0
	v_pk_mov_b32 v[60:61], 0, 0
	v_pk_mov_b32 v[62:63], 0, 0
	v_pk_mov_b32 v[64:65], 0, 0
	v_pk_mov_b32 v[66:67], 0, 0
	v_pk_mov_b32 v[68:69], 0, 0
	v_pk_mov_b32 v[70:71], 0, 0
	v_pk_mov_b32 v[72:73], 0, 0
	v_pk_mov_b32 v[74:75], 0, 0
	v_pk_mov_b32 v[76:77], 0, 0
	v_pk_mov_b32 v[78:79], 0, 0
	v_pk_mov_b32 v[84:85], 0, 0
	v_pk_mov_b32 v[86:87], 0, 0
	v_pk_mov_b32 v[92:93], 0, 0
	v_pk_mov_b32 v[94:95], 0, 0
	v_pk_mov_b32 v[100:101], 0, 0
	v_pk_mov_b32 v[102:103], 0, 0
	v_pk_mov_b32 v[108:109], 0, 0
	v_pk_mov_b32 v[110:111], 0, 0
	v_pk_mov_b32 v[116:117], 0, 0
	v_pk_mov_b32 v[118:119], 0, 0
	v_pk_mov_b32 v[80:81], 0, 0
	v_pk_mov_b32 v[82:83], 0, 0
	v_pk_mov_b32 v[88:89], 0, 0
	v_pk_mov_b32 v[90:91], 0, 0
	v_pk_mov_b32 v[96:97], 0, 0
	v_pk_mov_b32 v[98:99], 0, 0
	v_pk_mov_b32 v[104:105], 0, 0
	v_pk_mov_b32 v[106:107], 0, 0
	v_pk_mov_b32 v[112:113], 0, 0
	v_pk_mov_b32 v[114:115], 0, 0
	v_pk_mov_b32 v[120:121], 0, 0
	v_pk_mov_b32 v[122:123], 0, 0
	v_pk_mov_b32 v[124:125], 0, 0
	v_pk_mov_b32 v[126:127], 0, 0
	v_pk_mov_b32 v[128:129], 0, 0
	v_pk_mov_b32 v[130:131], 0, 0
	s_branch .LBB0_937

.LBB0_1210:
	s_ashr_i32 s19, s18, 31
	s_lshl_b64 s[20:21], s[18:19], 15
	s_add_u32 s20, s44, s20
	s_addc_u32 s21, s45, s21
	s_and_b64 s[22:23], s[4:5], exec
	s_cselect_b32 s19, s21, s29
	s_cselect_b32 s34, s20, s28
	s_ashr_i32 s15, s14, 31
	s_lshl_b64 s[22:23], s[14:15], 15
	s_add_u32 s22, s46, s22
	s_addc_u32 s23, s47, s23
	s_and_b64 s[30:31], s[4:5], exec
	s_cselect_b32 s15, s23, s27
	s_cselect_b32 s35, s22, s26
	s_add_u32 s48, s26, 0x80000
	s_addc_u32 s49, s27, 0
	s_add_u32 s26, s28, 0x204000
	v_mov_b32_e32 v4, 0
	s_addc_u32 s27, s29, 0
	s_mov_b32 s58, -2
	v_mov_b32_e32 v5, v4
	v_pk_mov_b32 v[6:7], 0, 0
	v_pk_mov_b32 v[8:9], 0, 0
	v_pk_mov_b32 v[10:11], 0, 0
	v_pk_mov_b32 v[20:21], 0, 0
	v_pk_mov_b32 v[22:23], 0, 0
	v_pk_mov_b32 v[24:25], 0, 0
	v_pk_mov_b32 v[26:27], 0, 0
	v_pk_mov_b32 v[36:37], 0, 0
	v_pk_mov_b32 v[38:39], 0, 0
	v_pk_mov_b32 v[40:41], 0, 0
	v_pk_mov_b32 v[42:43], 0, 0
	v_pk_mov_b32 v[52:53], 0, 0
	v_pk_mov_b32 v[54:55], 0, 0
	v_pk_mov_b32 v[56:57], 0, 0
	v_pk_mov_b32 v[58:59], 0, 0
	v_pk_mov_b32 v[12:13], 0, 0
	v_pk_mov_b32 v[14:15], 0, 0
	v_pk_mov_b32 v[16:17], 0, 0
	v_pk_mov_b32 v[18:19], 0, 0
	v_pk_mov_b32 v[28:29], 0, 0
	v_pk_mov_b32 v[30:31], 0, 0
	v_pk_mov_b32 v[32:33], 0, 0
	v_pk_mov_b32 v[34:35], 0, 0
	v_pk_mov_b32 v[44:45], 0, 0
	v_pk_mov_b32 v[46:47], 0, 0
	v_pk_mov_b32 v[48:49], 0, 0
	v_pk_mov_b32 v[50:51], 0, 0
	v_pk_mov_b32 v[60:61], 0, 0
	v_pk_mov_b32 v[62:63], 0, 0
	v_pk_mov_b32 v[64:65], 0, 0
	v_pk_mov_b32 v[66:67], 0, 0
	v_pk_mov_b32 v[84:85], 0, 0
	v_pk_mov_b32 v[86:87], 0, 0
	v_pk_mov_b32 v[88:89], 0, 0
	v_pk_mov_b32 v[90:91], 0, 0
	v_pk_mov_b32 v[92:93], 0, 0
	v_pk_mov_b32 v[94:95], 0, 0
	v_pk_mov_b32 v[100:101], 0, 0
	v_pk_mov_b32 v[102:103], 0, 0
	v_pk_mov_b32 v[116:117], 0, 0
	v_pk_mov_b32 v[118:119], 0, 0
	v_pk_mov_b32 v[120:121], 0, 0
	v_pk_mov_b32 v[122:123], 0, 0
	v_pk_mov_b32 v[124:125], 0, 0
	v_pk_mov_b32 v[126:127], 0, 0
	v_pk_mov_b32 v[132:133], 0, 0
	v_pk_mov_b32 v[134:135], 0, 0
	v_pk_mov_b32 v[96:97], 0, 0
	v_pk_mov_b32 v[98:99], 0, 0
	v_pk_mov_b32 v[104:105], 0, 0
	v_pk_mov_b32 v[106:107], 0, 0
	v_pk_mov_b32 v[108:109], 0, 0
	v_pk_mov_b32 v[110:111], 0, 0
	v_pk_mov_b32 v[112:113], 0, 0
	v_pk_mov_b32 v[114:115], 0, 0
	v_pk_mov_b32 v[128:129], 0, 0
	v_pk_mov_b32 v[130:131], 0, 0
	v_pk_mov_b32 v[136:137], 0, 0
	v_pk_mov_b32 v[138:139], 0, 0
	v_pk_mov_b32 v[140:141], 0, 0
	v_pk_mov_b32 v[142:143], 0, 0
	v_pk_mov_b32 v[144:145], 0, 0
	v_pk_mov_b32 v[146:147], 0, 0
